# NSA mode-2 lean iteration: own head, DMA in QK shadow, no max tree (row-sum threshold)
# speedup vs baseline: 1.0197x; 1.0197x over previous
.LBB0_1463:
	s_cmp_eq_u32 s63, 2
	s_cbranch_scc0 .Lm2_no
	s_add_i32 s98, s54, 1
	s_cmp_ge_i32 s98, s53
	s_cbranch_scc1 .Lm2_no
	v_cmp_eq_f32_e64 s[18:19], s73, v222
	s_cmp_lg_u64 s[18:19], 0
	s_cbranch_scc1 .Lm2_no
	s_add_i32 s21, s38, s45
	s_and_b32 s20, s45, 2
	s_add_i32 s54, s54, 1
	s_mov_b64 s[94:95], 0
	s_lshl_b32 s30, s20, 13
	v_add_u32_e32 v8, s30, v169
	v_add_u32_e32 v3, s30, v193
	ds_read_b128 v[10:13], v8
	ds_read_b128 v[14:17], v8 offset:512
	ds_read_b128 v[174:177], v8 offset:2048
	ds_read_b128 v[178:181], v8 offset:2560
	ds_read_b128 v[182:185], v8 offset:4096
	ds_read_b128 v[186:189], v8 offset:4608
	ds_read_b128 v[228:231], v8 offset:6144
	ds_read_b128 v[232:235], v8 offset:6656
	s_lshr_b32 s0, s21, 5
	s_cmp_lt_u32 s0, 2
	s_cselect_b64 s[98:99], -1, 0
	s_bitcmp1_b32 s0, 0
	s_cselect_b64 s[0:1], -1, 0
	s_and_b32 s28, s21, 31
	v_cndmask_b32_e64 v5, v130, v131, s[0:1]
	v_cndmask_b32_e64 v6, v132, v133, s[0:1]
	v_cndmask_b32_e64 v5, v6, v5, s[98:99]
	v_lshrrev_b32_e32 v5, s28, v5
	v_and_b32_e32 v6, 1, v5
	v_bfe_u32 v9, v5, 1, 1
	v_xor_b32_e32 v7, 0x80000000, v222
	v_cmp_eq_u32_e32 vcc, 1, v6
	v_cmp_eq_u32_e64 s[98:99], 1, v9
	v_add_f32_e32 v4, v7, v201
	v_cndmask_b32_e32 v82, v4, v7, vcc
	v_cndmask_b32_e64 v50, v4, v7, s[98:99]
	v_mov_b32_e32 v83, v82
	v_mov_b32_e32 v84, v82
	v_mov_b32_e32 v85, v82
	v_mov_b32_e32 v86, v82
	v_mov_b32_e32 v87, v82
	v_mov_b32_e32 v88, v82
	v_mov_b32_e32 v89, v82
	v_mov_b32_e32 v90, v82
	v_mov_b32_e32 v91, v82
	v_mov_b32_e32 v92, v82
	v_mov_b32_e32 v93, v82
	v_mov_b32_e32 v94, v82
	v_mov_b32_e32 v95, v82
	v_mov_b32_e32 v96, v82
	v_mov_b32_e32 v97, v82
	v_mov_b32_e32 v51, v50
	s_waitcnt lgkmcnt(7)
	v_mfma_f32_32x32x16_bf16 v[98:113], v[10:13], v[114:117], v[82:97]
	ds_read_b128 v[10:13], v8 offset:8192
	v_mov_b32_e32 v52, v50
	v_mov_b32_e32 v53, v50
	v_mov_b32_e32 v54, v50
	v_mov_b32_e32 v55, v50
	v_mov_b32_e32 v56, v50
	v_mov_b32_e32 v57, v50
	v_mov_b32_e32 v58, v50
	v_mov_b32_e32 v59, v50
	v_mov_b32_e32 v60, v50
	v_mov_b32_e32 v61, v50
	s_waitcnt lgkmcnt(7)
	v_mfma_f32_32x32x16_bf16 v[82:97], v[14:17], v[114:117], v[82:97]
	ds_read_b128 v[14:17], v8 offset:8704
	v_mov_b32_e32 v62, v50
	v_mov_b32_e32 v63, v50
	v_mov_b32_e32 v64, v50
	v_mov_b32_e32 v65, v50
	s_mov_b32 s55, m0
	s_add_i32 s0, s21, 2
	s_ashr_i32 s1, s0, 31
	s_lshl_b64 s[0:1], s[0:1], 6
	s_add_u32 s0, s0, s84
	s_addc_u32 s1, s1, s85
	s_waitcnt lgkmcnt(7)
	v_mfma_f32_32x32x16_bf16 v[98:113], v[174:177], v[118:121], v[98:113]
	ds_read_b128 v[174:177], v8 offset:10240
	s_lshl_b64 s[0:1], s[0:1], 7
	s_add_u32 s28, s86, s0
	s_addc_u32 s29, s87, s1
	s_sub_i32 s31, s37, s30
	s_add_i32 s31, s31, 0x4000
	v_lshlrev_b32_e32 v4, 7, v138
	v_mov_b32_e32 v5, 0
	v_lshl_add_u64 v[4:5], s[28:29], 0, v[4:5]
	s_mov_b32 m0, s31
	s_movk_i32 s30, 0x80
	s_waitcnt lgkmcnt(7)
	v_mfma_f32_32x32x16_bf16 v[82:97], v[178:181], v[118:121], v[82:97]
	ds_read_b128 v[178:181], v8 offset:10752
	global_load_lds_dwordx4 v[4:5], off
	v_mad_u64_u32 v[226:227], vcc, v168, s30, v[134:135]
	s_add_i32 s31, s31, 0x8000
	v_lshl_add_u64 v[6:7], v[226:227], 0, s[0:1]
	s_mov_b32 m0, s31
	s_cmp_lt_i32 s45, s44
	global_load_lds_dwordx4 v[6:7], off
	s_waitcnt lgkmcnt(7)
	v_mfma_f32_32x32x16_bf16 v[98:113], v[182:185], v[122:125], v[98:113]
	ds_read_b128 v[182:185], v8 offset:12288
	s_cselect_b32 s98, 0x2000, 0
	s_add_u32 s28, s28, s98
	s_addc_u32 s29, s29, 0
	s_add_u32 s0, s0, s98
	s_addc_u32 s1, s1, 0
	s_sub_i32 s31, s31, 0x6000
	s_mov_b32 m0, s31
	v_lshl_add_u64 v[6:7], v[226:227], 0, s[0:1]
	v_lshlrev_b32_e32 v4, 7, v138
	v_mov_b32_e32 v5, 0
	s_waitcnt lgkmcnt(7)
	v_mfma_f32_32x32x16_bf16 v[82:97], v[186:189], v[122:125], v[82:97]
	ds_read_b128 v[186:189], v8 offset:12800
	v_lshl_add_u64 v[4:5], s[28:29], 0, v[4:5]
	global_load_lds_dwordx4 v[4:5], off
	s_add_i32 s31, s31, 0x8000
	s_mov_b32 m0, s31
	s_nop 0
	global_load_lds_dwordx4 v[6:7], off
	s_waitcnt lgkmcnt(7)
	v_mfma_f32_32x32x16_bf16 v[98:113], v[228:231], v[126:129], v[98:113]
	ds_read_b128 v[228:231], v8 offset:14336
	s_mov_b32 m0, s55
	s_waitcnt lgkmcnt(7)
	v_mfma_f32_32x32x16_bf16 v[82:97], v[232:235], v[126:129], v[82:97]
	ds_read_b128 v[232:235], v8 offset:14848
	s_waitcnt lgkmcnt(7)
	v_mfma_f32_32x32x16_bf16 v[66:81], v[10:13], v[114:117], v[50:65]
	ds_read_b64_tr_b16 v[10:11], v3 offset:32768
	ds_read_b64_tr_b16 v[12:13], v3 offset:33280
	s_waitcnt lgkmcnt(8)
	v_mfma_f32_32x32x16_bf16 v[50:65], v[14:17], v[114:117], v[50:65]
	ds_read_b64_tr_b16 v[14:15], v3 offset:36864
	ds_read_b64_tr_b16 v[16:17], v3 offset:37376
	s_waitcnt lgkmcnt(9)
	v_mfma_f32_32x32x16_bf16 v[66:81], v[174:177], v[118:121], v[66:81]
	ds_read_b64_tr_b16 v[174:175], v3 offset:33792
	ds_read_b64_tr_b16 v[176:177], v3 offset:34304
	v_exp_f32_e32 v98, v98
	v_exp_f32_e32 v99, v99
	v_exp_f32_e32 v100, v100
	v_exp_f32_e32 v101, v101
	v_exp_f32_e32 v102, v102
	s_waitcnt lgkmcnt(10)
	v_mfma_f32_32x32x16_bf16 v[50:65], v[178:181], v[118:121], v[50:65]
	ds_read_b64_tr_b16 v[178:179], v3 offset:37888
	ds_read_b64_tr_b16 v[180:181], v3 offset:38400
	v_exp_f32_e32 v103, v103
	v_exp_f32_e32 v104, v104
	v_exp_f32_e32 v105, v105
	v_cvt_pk_bf16_f32 v236, v98, v99
	v_cvt_pk_bf16_f32 v237, v100, v101
	v_cvt_pk_bf16_f32 v238, v102, v103
	v_cvt_pk_bf16_f32 v239, v104, v105
	s_waitcnt lgkmcnt(11)
	v_mfma_f32_32x32x16_bf16 v[66:81], v[182:185], v[122:125], v[66:81]
	ds_read_b64_tr_b16 v[182:183], v3 offset:34816
	ds_read_b64_tr_b16 v[184:185], v3 offset:35328
	v_exp_f32_e32 v106, v106
	v_exp_f32_e32 v107, v107
	v_exp_f32_e32 v108, v108
	v_exp_f32_e32 v109, v109
	v_exp_f32_e32 v110, v110
	s_waitcnt lgkmcnt(12)
	v_mfma_f32_32x32x16_bf16 v[50:65], v[186:189], v[122:125], v[50:65]
	ds_read_b64_tr_b16 v[186:187], v3 offset:38912
	ds_read_b64_tr_b16 v[188:189], v3 offset:39424
	v_exp_f32_e32 v111, v111
	v_exp_f32_e32 v112, v112
	v_exp_f32_e32 v113, v113
	v_cvt_pk_bf16_f32 v240, v106, v107
	v_cvt_pk_bf16_f32 v241, v108, v109
	v_cvt_pk_bf16_f32 v242, v110, v111
	v_cvt_pk_bf16_f32 v243, v112, v113
	s_waitcnt lgkmcnt(13)
	v_mfma_f32_32x32x16_bf16 v[66:81], v[228:231], v[126:129], v[66:81]
	ds_read_b64_tr_b16 v[228:229], v3 offset:35840
	ds_read_b64_tr_b16 v[230:231], v3 offset:36352
	v_exp_f32_e32 v82, v82
	v_exp_f32_e32 v83, v83
	v_exp_f32_e32 v84, v84
	v_exp_f32_e32 v85, v85
	v_exp_f32_e32 v86, v86
	s_waitcnt lgkmcnt(14)
	v_mfma_f32_32x32x16_bf16 v[50:65], v[232:235], v[126:129], v[50:65]
	s_waitcnt lgkmcnt(13)
	ds_read_b64_tr_b16 v[232:233], v3 offset:39936
	ds_read_b64_tr_b16 v[234:235], v3 offset:40448
	v_exp_f32_e32 v87, v87
	v_exp_f32_e32 v88, v88
	v_exp_f32_e32 v89, v89
	v_cvt_pk_bf16_f32 v244, v82, v83
	v_cvt_pk_bf16_f32 v245, v84, v85
	v_cvt_pk_bf16_f32 v246, v86, v87
	v_cvt_pk_bf16_f32 v247, v88, v89
	s_waitcnt lgkmcnt(14)
	v_mfma_f32_32x32x16_bf16 v[34:49], v[236:239], v[10:13], v[34:49]
	s_waitcnt lgkmcnt(13)
	ds_read_b64_tr_b16 v[10:11], v3 offset:40960
	ds_read_b64_tr_b16 v[12:13], v3 offset:41472
	v_exp_f32_e32 v90, v90
	v_exp_f32_e32 v91, v91
	v_exp_f32_e32 v92, v92
	v_exp_f32_e32 v93, v93
	v_exp_f32_e32 v94, v94
	s_waitcnt lgkmcnt(14)
	v_mfma_f32_32x32x16_bf16 v[18:33], v[236:239], v[14:17], v[18:33]
	s_waitcnt lgkmcnt(13)
	ds_read_b64_tr_b16 v[14:15], v3 offset:45056
	ds_read_b64_tr_b16 v[16:17], v3 offset:45568
	v_exp_f32_e32 v95, v95
	v_exp_f32_e32 v96, v96
	v_exp_f32_e32 v97, v97
	v_cvt_pk_bf16_f32 v248, v90, v91
	v_cvt_pk_bf16_f32 v249, v92, v93
	v_cvt_pk_bf16_f32 v250, v94, v95
	v_cvt_pk_bf16_f32 v251, v96, v97
	s_waitcnt lgkmcnt(14)
	v_mfma_f32_32x32x16_bf16 v[34:49], v[240:243], v[174:177], v[34:49]
	s_waitcnt lgkmcnt(13)
	ds_read_b64_tr_b16 v[174:175], v3 offset:41984
	ds_read_b64_tr_b16 v[176:177], v3 offset:42496
	v_exp_f32_e32 v66, v66
	v_exp_f32_e32 v67, v67
	v_exp_f32_e32 v68, v68
	v_exp_f32_e32 v69, v69
	v_exp_f32_e32 v70, v70
	s_waitcnt lgkmcnt(14)
	v_mfma_f32_32x32x16_bf16 v[18:33], v[240:243], v[178:181], v[18:33]
	s_waitcnt lgkmcnt(13)
	ds_read_b64_tr_b16 v[178:179], v3 offset:46080
	ds_read_b64_tr_b16 v[180:181], v3 offset:46592
	v_exp_f32_e32 v71, v71
	v_exp_f32_e32 v72, v72
	v_exp_f32_e32 v73, v73
	v_cvt_pk_bf16_f32 v236, v66, v67
	v_cvt_pk_bf16_f32 v237, v68, v69
	v_cvt_pk_bf16_f32 v238, v70, v71
	v_cvt_pk_bf16_f32 v239, v72, v73
	s_waitcnt lgkmcnt(14)
	v_mfma_f32_32x32x16_bf16 v[34:49], v[244:247], v[182:185], v[34:49]
	s_waitcnt lgkmcnt(13)
	ds_read_b64_tr_b16 v[182:183], v3 offset:43008
	ds_read_b64_tr_b16 v[184:185], v3 offset:43520
	v_exp_f32_e32 v74, v74
	v_exp_f32_e32 v75, v75
	v_exp_f32_e32 v76, v76
	v_exp_f32_e32 v77, v77
	v_exp_f32_e32 v78, v78
	s_waitcnt lgkmcnt(14)
	v_mfma_f32_32x32x16_bf16 v[18:33], v[244:247], v[186:189], v[18:33]
	s_waitcnt lgkmcnt(13)
	ds_read_b64_tr_b16 v[186:187], v3 offset:47104
	ds_read_b64_tr_b16 v[188:189], v3 offset:47616
	v_exp_f32_e32 v79, v79
	v_exp_f32_e32 v80, v80
	v_exp_f32_e32 v81, v81
	v_cvt_pk_bf16_f32 v240, v74, v75
	v_cvt_pk_bf16_f32 v241, v76, v77
	v_cvt_pk_bf16_f32 v242, v78, v79
	v_cvt_pk_bf16_f32 v243, v80, v81
	s_waitcnt lgkmcnt(14)
	v_mfma_f32_32x32x16_bf16 v[34:49], v[248:251], v[228:231], v[34:49]
	s_waitcnt lgkmcnt(13)
	ds_read_b64_tr_b16 v[228:229], v3 offset:44032
	ds_read_b64_tr_b16 v[230:231], v3 offset:44544
	v_exp_f32_e32 v50, v50
	v_exp_f32_e32 v51, v51
	v_exp_f32_e32 v52, v52
	v_exp_f32_e32 v53, v53
	v_exp_f32_e32 v54, v54
	s_waitcnt lgkmcnt(14)
	v_mfma_f32_32x32x16_bf16 v[18:33], v[248:251], v[232:235], v[18:33]
	s_waitcnt lgkmcnt(13)
	ds_read_b64_tr_b16 v[232:233], v3 offset:48128
	ds_read_b64_tr_b16 v[234:235], v3 offset:48640
	v_exp_f32_e32 v55, v55
	v_exp_f32_e32 v56, v56
	v_exp_f32_e32 v57, v57
	v_cvt_pk_bf16_f32 v244, v50, v51
	v_cvt_pk_bf16_f32 v245, v52, v53
	v_cvt_pk_bf16_f32 v246, v54, v55
	v_cvt_pk_bf16_f32 v247, v56, v57
	s_waitcnt lgkmcnt(14)
	v_mfma_f32_32x32x16_bf16 v[34:49], v[236:239], v[10:13], v[34:49]
	v_exp_f32_e32 v58, v58
	v_exp_f32_e32 v59, v59
	v_exp_f32_e32 v60, v60
	v_exp_f32_e32 v61, v61
	v_exp_f32_e32 v62, v62
	s_waitcnt lgkmcnt(12)
	v_mfma_f32_32x32x16_bf16 v[18:33], v[236:239], v[14:17], v[18:33]
	v_exp_f32_e32 v63, v63
	v_exp_f32_e32 v64, v64
	v_exp_f32_e32 v65, v65
	v_cvt_pk_bf16_f32 v248, v58, v59
	v_cvt_pk_bf16_f32 v249, v60, v61
	v_cvt_pk_bf16_f32 v250, v62, v63
	v_cvt_pk_bf16_f32 v251, v64, v65
	s_waitcnt lgkmcnt(10)
	v_mfma_f32_32x32x16_bf16 v[34:49], v[240:243], v[174:177], v[34:49]
	v_add_f32_e32 v4, v98, v100
	v_add_f32_e32 v9, v99, v101
	v_add_f32_e32 v6, v82, v84
	v_add_f32_e32 v7, v83, v85
	v_add_f32_e32 v4, v4, v102
	v_add_f32_e32 v9, v9, v103
	v_add_f32_e32 v6, v6, v86
	v_add_f32_e32 v7, v7, v87
	v_add_f32_e32 v4, v4, v104
	v_add_f32_e32 v9, v9, v105
	s_waitcnt lgkmcnt(8)
	v_mfma_f32_32x32x16_bf16 v[18:33], v[240:243], v[178:181], v[18:33]
	v_add_f32_e32 v6, v6, v88
	v_add_f32_e32 v7, v7, v89
	v_add_f32_e32 v4, v4, v106
	v_add_f32_e32 v9, v9, v107
	v_add_f32_e32 v6, v6, v90
	v_add_f32_e32 v7, v7, v91
	v_add_f32_e32 v4, v4, v108
	v_add_f32_e32 v9, v9, v109
	v_add_f32_e32 v6, v6, v92
	v_add_f32_e32 v7, v7, v93
	s_waitcnt lgkmcnt(6)
	v_mfma_f32_32x32x16_bf16 v[34:49], v[244:247], v[182:185], v[34:49]
	v_add_f32_e32 v4, v4, v110
	v_add_f32_e32 v9, v9, v111
	v_add_f32_e32 v6, v6, v94
	v_add_f32_e32 v7, v7, v95
	v_add_f32_e32 v4, v4, v112
	v_add_f32_e32 v9, v9, v113
	v_add_f32_e32 v6, v6, v96
	v_add_f32_e32 v7, v7, v97
	v_add_f32_e32 v6, v6, v7
	v_add_f32_e32 v4, v4, v9
	s_waitcnt lgkmcnt(4)
	v_mfma_f32_32x32x16_bf16 v[18:33], v[244:247], v[186:189], v[18:33]
	v_add_f32_e32 v4, v6, v4
	v_mov_b32_e32 v5, v4
	v_add_f32_e32 v225, v225, v4
	v_add_f32_e32 v4, v66, v68
	v_add_f32_e32 v9, v67, v69
	v_add_f32_e32 v6, v50, v52
	v_add_f32_e32 v7, v51, v53
	v_add_f32_e32 v4, v4, v70
	v_add_f32_e32 v9, v9, v71
	v_add_f32_e32 v6, v6, v54
	s_waitcnt lgkmcnt(2)
	v_mfma_f32_32x32x16_bf16 v[34:49], v[248:251], v[228:231], v[34:49]
	v_add_f32_e32 v7, v7, v55
	v_add_f32_e32 v4, v4, v72
	v_add_f32_e32 v9, v9, v73
	v_add_f32_e32 v6, v6, v56
	v_add_f32_e32 v7, v7, v57
	v_add_f32_e32 v4, v4, v74
	v_add_f32_e32 v9, v9, v75
	v_add_f32_e32 v6, v6, v58
	v_add_f32_e32 v7, v7, v59
	v_add_f32_e32 v4, v4, v76
	s_waitcnt lgkmcnt(0)
	v_mfma_f32_32x32x16_bf16 v[18:33], v[248:251], v[232:235], v[18:33]
	v_add_f32_e32 v9, v9, v77
	v_add_f32_e32 v6, v6, v60
	v_add_f32_e32 v7, v7, v61
	v_add_f32_e32 v4, v4, v78
	v_add_f32_e32 v9, v9, v79
	v_add_f32_e32 v6, v6, v62
	v_add_f32_e32 v7, v7, v63
	v_add_f32_e32 v4, v4, v80
	v_add_f32_e32 v9, v9, v81
	v_add_f32_e32 v6, v6, v64
	v_add_f32_e32 v7, v7, v65
	v_add_f32_e32 v6, v6, v7
	v_add_f32_e32 v4, v4, v9
	v_add_f32_e32 v4, v6, v4
	v_add_f32_e32 v225, v225, v4
	s_mov_b64 s[20:21], 0
	s_mov_b32 s30, 0x437f0000
	v_cmp_nge_f32_e32 vcc, s30, v5
	v_cmp_nge_f32_e64 s[98:99], s30, v4
	s_mov_b64 s[28:29], 0
	s_mov_b64 s[0:1], 0
	s_or_b64 s[98:99], vcc, s[98:99]
	s_cbranch_scc0 .LBB0_1492
	v_max3_f32 v5, v98, v99, v100
	v_max3_f32 v6, v106, v107, v108
	v_max3_f32 v9, v82, v83, v84
	v_max3_f32 v227, v90, v91, v92
	v_max3_f32 v5, v5, v101, v102
	v_max3_f32 v6, v6, v109, v110
	v_max3_f32 v9, v9, v85, v86
	v_max3_f32 v227, v227, v93, v94
	v_max3_f32 v5, v5, v103, v104
	v_max3_f32 v6, v6, v111, v112
	v_max3_f32 v9, v9, v87, v88
	v_max3_f32 v227, v227, v95, v96
	v_max3_f32 v5, v5, v105, v113
	v_max3_f32 v9, v9, v89, v97
	v_max3_f32 v5, v5, v6, v9
	v_max_f32_e32 v5, v5, v227
	v_mov_b32_e32 v6, v5
	s_nop 1
	v_permlane32_swap_b32_e32 v5, v6
	v_max_f32_e32 v5, v5, v6
	v_log_f32_e32 v5, v5
	s_nop 0
	v_cmp_lt_f32_e32 vcc, s74, v5
	s_and_b64 s[28:29], s[18:19], vcc
	v_cmp_lt_f32_e32 vcc, s75, v5
	s_or_b64 s[28:29], vcc, s[28:29]
	s_nop 0
	v_cndmask_b32_e64 v252, 0, v5, s[28:29]
	s_cselect_b64 s[28:29], -1, 0
	v_max3_f32 v5, v66, v67, v68
	v_max3_f32 v6, v74, v75, v76
	v_max3_f32 v9, v50, v51, v52
	v_max3_f32 v227, v58, v59, v60
	v_max3_f32 v5, v5, v69, v70
	v_max3_f32 v6, v6, v77, v78
	v_max3_f32 v9, v9, v53, v54
	v_max3_f32 v227, v227, v61, v62
	v_max3_f32 v5, v5, v71, v72
	v_max3_f32 v6, v6, v79, v80
	v_max3_f32 v9, v9, v55, v56
	v_max3_f32 v227, v227, v63, v64
	v_max3_f32 v5, v5, v73, v81
	v_max3_f32 v9, v9, v57, v65
	v_max3_f32 v5, v5, v6, v9
	v_max_f32_e32 v5, v5, v227
	v_mov_b32_e32 v6, v5
	s_nop 1
	v_permlane32_swap_b32_e32 v5, v6
	v_max_f32_e32 v5, v5, v6
	v_log_f32_e32 v5, v5
	s_nop 0
	v_cmp_lt_f32_e32 vcc, s74, v5
	s_and_b64 s[0:1], s[18:19], vcc
	v_cmp_lt_f32_e32 vcc, s75, v5
	s_or_b64 s[0:1], vcc, s[0:1]
	s_nop 0
	v_cndmask_b32_e64 v101, 0, v5, s[0:1]
	s_cselect_b64 s[0:1], -1, 0
	v_mov_b32_e32 v228, v252
	s_branch .LBB0_1492

.LBB0_1476:
	s_cmp_lt_u32 s63, 2
	s_cbranch_scc1 .Lhb_orig
	s_or_b64 s[98:99], s[0:1], s[96:97]
	s_cbranch_scc1 .Lhb_orig
	v_cmp_eq_f32_e64 s[18:19], s73, v222
	s_cmp_lg_u64 s[18:19], 0
	s_cbranch_scc1 .Lhb_full
	s_lshl_b32 s30, s20, 13
	v_add_u32_e32 v8, s30, v169
	v_add_u32_e32 v3, s30, v193
	ds_read_b128 v[10:13], v8
	ds_read_b128 v[14:17], v8 offset:512
	ds_read_b128 v[174:177], v8 offset:2048
	ds_read_b128 v[178:181], v8 offset:2560
	ds_read_b128 v[182:185], v8 offset:4096
	ds_read_b128 v[186:189], v8 offset:4608
	ds_read_b128 v[228:231], v8 offset:6144
	ds_read_b128 v[232:235], v8 offset:6656
	v_cmp_eq_f32_e64 s[18:19], s73, v222
	s_mov_b64 s[20:21], 0
	s_nop 0
	v_cndmask_b32_e64 v7, -v222, v204, s[18:19]
	v_add_f32_e32 v82, v7, v9
	v_add_f32_e32 v50, v7, v4
	v_mov_b32_e32 v83, v82
	v_mov_b32_e32 v84, v82
	v_mov_b32_e32 v85, v82
	v_mov_b32_e32 v86, v82
	v_mov_b32_e32 v87, v82
	v_mov_b32_e32 v88, v82
	v_mov_b32_e32 v89, v82
	v_mov_b32_e32 v90, v82
	v_mov_b32_e32 v91, v82
	v_mov_b32_e32 v92, v82
	v_mov_b32_e32 v93, v82
	v_mov_b32_e32 v94, v82
	v_mov_b32_e32 v95, v82
	v_mov_b32_e32 v96, v82
	v_mov_b32_e32 v97, v82
	v_mov_b32_e32 v51, v50
	s_waitcnt lgkmcnt(7)
	v_mfma_f32_32x32x16_bf16 v[98:113], v[10:13], v[114:117], v[82:97]
	ds_read_b128 v[10:13], v8 offset:8192
	v_mov_b32_e32 v52, v50
	v_mov_b32_e32 v53, v50
	v_mov_b32_e32 v54, v50
	v_mov_b32_e32 v55, v50
	v_mov_b32_e32 v56, v50
	v_mov_b32_e32 v57, v50
	v_mov_b32_e32 v58, v50
	v_mov_b32_e32 v59, v50
	v_mov_b32_e32 v60, v50
	v_mov_b32_e32 v61, v50
	s_waitcnt lgkmcnt(7)
	v_mfma_f32_32x32x16_bf16 v[82:97], v[14:17], v[114:117], v[82:97]
	ds_read_b128 v[14:17], v8 offset:8704
	v_mov_b32_e32 v62, v50
	v_mov_b32_e32 v63, v50
	v_mov_b32_e32 v64, v50
	v_mov_b32_e32 v65, v50
	s_waitcnt lgkmcnt(7)
	v_mfma_f32_32x32x16_bf16 v[98:113], v[174:177], v[118:121], v[98:113]
	ds_read_b128 v[174:177], v8 offset:10240
	s_waitcnt lgkmcnt(7)
	v_mfma_f32_32x32x16_bf16 v[82:97], v[178:181], v[118:121], v[82:97]
	ds_read_b128 v[178:181], v8 offset:10752
	s_waitcnt lgkmcnt(7)
	v_mfma_f32_32x32x16_bf16 v[98:113], v[182:185], v[122:125], v[98:113]
	ds_read_b128 v[182:185], v8 offset:12288
	s_waitcnt lgkmcnt(7)
	v_mfma_f32_32x32x16_bf16 v[82:97], v[186:189], v[122:125], v[82:97]
	ds_read_b128 v[186:189], v8 offset:12800
	s_waitcnt lgkmcnt(7)
	v_mfma_f32_32x32x16_bf16 v[98:113], v[228:231], v[126:129], v[98:113]
	ds_read_b128 v[228:231], v8 offset:14336
	s_waitcnt lgkmcnt(7)
	v_mfma_f32_32x32x16_bf16 v[82:97], v[232:235], v[126:129], v[82:97]
	ds_read_b128 v[232:235], v8 offset:14848
	s_waitcnt lgkmcnt(7)
	v_mfma_f32_32x32x16_bf16 v[66:81], v[10:13], v[114:117], v[50:65]
	ds_read_b64_tr_b16 v[10:11], v3 offset:32768
	ds_read_b64_tr_b16 v[12:13], v3 offset:33280
	s_waitcnt lgkmcnt(8)
	v_mfma_f32_32x32x16_bf16 v[50:65], v[14:17], v[114:117], v[50:65]
	ds_read_b64_tr_b16 v[14:15], v3 offset:36864
	ds_read_b64_tr_b16 v[16:17], v3 offset:37376
	s_waitcnt lgkmcnt(9)
	v_mfma_f32_32x32x16_bf16 v[66:81], v[174:177], v[118:121], v[66:81]
	ds_read_b64_tr_b16 v[174:175], v3 offset:33792
	ds_read_b64_tr_b16 v[176:177], v3 offset:34304
	v_exp_f32_e32 v98, v98
	v_exp_f32_e32 v99, v99
	v_exp_f32_e32 v100, v100
	v_exp_f32_e32 v101, v101
	v_exp_f32_e32 v102, v102
	s_waitcnt lgkmcnt(10)
	v_mfma_f32_32x32x16_bf16 v[50:65], v[178:181], v[118:121], v[50:65]
	ds_read_b64_tr_b16 v[178:179], v3 offset:37888
	ds_read_b64_tr_b16 v[180:181], v3 offset:38400
	v_exp_f32_e32 v103, v103
	v_exp_f32_e32 v104, v104
	v_exp_f32_e32 v105, v105
	v_cvt_pk_bf16_f32 v236, v98, v99
	v_cvt_pk_bf16_f32 v237, v100, v101
	v_cvt_pk_bf16_f32 v238, v102, v103
	v_cvt_pk_bf16_f32 v239, v104, v105
	s_waitcnt lgkmcnt(11)
	v_mfma_f32_32x32x16_bf16 v[66:81], v[182:185], v[122:125], v[66:81]
	ds_read_b64_tr_b16 v[182:183], v3 offset:34816
	ds_read_b64_tr_b16 v[184:185], v3 offset:35328
	v_exp_f32_e32 v106, v106
	v_exp_f32_e32 v107, v107
	v_exp_f32_e32 v108, v108
	v_exp_f32_e32 v109, v109
	v_exp_f32_e32 v110, v110
	s_waitcnt lgkmcnt(12)
	v_mfma_f32_32x32x16_bf16 v[50:65], v[186:189], v[122:125], v[50:65]
	ds_read_b64_tr_b16 v[186:187], v3 offset:38912
	ds_read_b64_tr_b16 v[188:189], v3 offset:39424
	v_exp_f32_e32 v111, v111
	v_exp_f32_e32 v112, v112
	v_exp_f32_e32 v113, v113
	v_cvt_pk_bf16_f32 v240, v106, v107
	v_cvt_pk_bf16_f32 v241, v108, v109
	v_cvt_pk_bf16_f32 v242, v110, v111
	v_cvt_pk_bf16_f32 v243, v112, v113
	s_waitcnt lgkmcnt(13)
	v_mfma_f32_32x32x16_bf16 v[66:81], v[228:231], v[126:129], v[66:81]
	ds_read_b64_tr_b16 v[228:229], v3 offset:35840
	ds_read_b64_tr_b16 v[230:231], v3 offset:36352
	v_exp_f32_e32 v82, v82
	v_exp_f32_e32 v83, v83
	v_exp_f32_e32 v84, v84
	v_exp_f32_e32 v85, v85
	v_exp_f32_e32 v86, v86
	s_waitcnt lgkmcnt(14)
	v_mfma_f32_32x32x16_bf16 v[50:65], v[232:235], v[126:129], v[50:65]
	s_waitcnt lgkmcnt(13)
	ds_read_b64_tr_b16 v[232:233], v3 offset:39936
	ds_read_b64_tr_b16 v[234:235], v3 offset:40448
	v_exp_f32_e32 v87, v87
	v_exp_f32_e32 v88, v88
	v_exp_f32_e32 v89, v89
	v_cvt_pk_bf16_f32 v244, v82, v83
	v_cvt_pk_bf16_f32 v245, v84, v85
	v_cvt_pk_bf16_f32 v246, v86, v87
	v_cvt_pk_bf16_f32 v247, v88, v89
	s_waitcnt lgkmcnt(14)
	v_mfma_f32_32x32x16_bf16 v[34:49], v[236:239], v[10:13], v[34:49]
	s_waitcnt lgkmcnt(13)
	ds_read_b64_tr_b16 v[10:11], v3 offset:40960
	ds_read_b64_tr_b16 v[12:13], v3 offset:41472
	v_exp_f32_e32 v90, v90
	v_exp_f32_e32 v91, v91
	v_exp_f32_e32 v92, v92
	v_exp_f32_e32 v93, v93
	v_exp_f32_e32 v94, v94
	s_waitcnt lgkmcnt(14)
	v_mfma_f32_32x32x16_bf16 v[18:33], v[236:239], v[14:17], v[18:33]
	s_waitcnt lgkmcnt(13)
	ds_read_b64_tr_b16 v[14:15], v3 offset:45056
	ds_read_b64_tr_b16 v[16:17], v3 offset:45568
	v_exp_f32_e32 v95, v95
	v_exp_f32_e32 v96, v96
	v_exp_f32_e32 v97, v97
	v_cvt_pk_bf16_f32 v248, v90, v91
	v_cvt_pk_bf16_f32 v249, v92, v93
	v_cvt_pk_bf16_f32 v250, v94, v95
	v_cvt_pk_bf16_f32 v251, v96, v97
	s_waitcnt lgkmcnt(14)
	v_mfma_f32_32x32x16_bf16 v[34:49], v[240:243], v[174:177], v[34:49]
	s_waitcnt lgkmcnt(13)
	ds_read_b64_tr_b16 v[174:175], v3 offset:41984
	ds_read_b64_tr_b16 v[176:177], v3 offset:42496
	v_exp_f32_e32 v66, v66
	v_exp_f32_e32 v67, v67
	v_exp_f32_e32 v68, v68
	v_exp_f32_e32 v69, v69
	v_exp_f32_e32 v70, v70
	s_waitcnt lgkmcnt(14)
	v_mfma_f32_32x32x16_bf16 v[18:33], v[240:243], v[178:181], v[18:33]
	s_waitcnt lgkmcnt(13)
	ds_read_b64_tr_b16 v[178:179], v3 offset:46080
	ds_read_b64_tr_b16 v[180:181], v3 offset:46592
	v_exp_f32_e32 v71, v71
	v_exp_f32_e32 v72, v72
	v_exp_f32_e32 v73, v73
	v_cvt_pk_bf16_f32 v236, v66, v67
	v_cvt_pk_bf16_f32 v237, v68, v69
	v_cvt_pk_bf16_f32 v238, v70, v71
	v_cvt_pk_bf16_f32 v239, v72, v73
	s_waitcnt lgkmcnt(14)
	v_mfma_f32_32x32x16_bf16 v[34:49], v[244:247], v[182:185], v[34:49]
	s_waitcnt lgkmcnt(13)
	ds_read_b64_tr_b16 v[182:183], v3 offset:43008
	ds_read_b64_tr_b16 v[184:185], v3 offset:43520
	v_exp_f32_e32 v74, v74
	v_exp_f32_e32 v75, v75
	v_exp_f32_e32 v76, v76
	v_exp_f32_e32 v77, v77
	v_exp_f32_e32 v78, v78
	s_waitcnt lgkmcnt(14)
	v_mfma_f32_32x32x16_bf16 v[18:33], v[244:247], v[186:189], v[18:33]
	s_waitcnt lgkmcnt(13)
	ds_read_b64_tr_b16 v[186:187], v3 offset:47104
	ds_read_b64_tr_b16 v[188:189], v3 offset:47616
	v_exp_f32_e32 v79, v79
	v_exp_f32_e32 v80, v80
	v_exp_f32_e32 v81, v81
	v_cvt_pk_bf16_f32 v240, v74, v75
	v_cvt_pk_bf16_f32 v241, v76, v77
	v_cvt_pk_bf16_f32 v242, v78, v79
	v_cvt_pk_bf16_f32 v243, v80, v81
	s_waitcnt lgkmcnt(14)
	v_mfma_f32_32x32x16_bf16 v[34:49], v[248:251], v[228:231], v[34:49]
	s_waitcnt lgkmcnt(13)
	ds_read_b64_tr_b16 v[228:229], v3 offset:44032
	ds_read_b64_tr_b16 v[230:231], v3 offset:44544
	v_exp_f32_e32 v50, v50
	v_exp_f32_e32 v51, v51
	v_exp_f32_e32 v52, v52
	v_exp_f32_e32 v53, v53
	v_exp_f32_e32 v54, v54
	s_waitcnt lgkmcnt(14)
	v_mfma_f32_32x32x16_bf16 v[18:33], v[248:251], v[232:235], v[18:33]
	s_waitcnt lgkmcnt(13)
	ds_read_b64_tr_b16 v[232:233], v3 offset:48128
	ds_read_b64_tr_b16 v[234:235], v3 offset:48640
	v_exp_f32_e32 v55, v55
	v_exp_f32_e32 v56, v56
	v_exp_f32_e32 v57, v57
	v_cvt_pk_bf16_f32 v244, v50, v51
	v_cvt_pk_bf16_f32 v245, v52, v53
	v_cvt_pk_bf16_f32 v246, v54, v55
	v_cvt_pk_bf16_f32 v247, v56, v57
	s_waitcnt lgkmcnt(14)
	v_mfma_f32_32x32x16_bf16 v[34:49], v[236:239], v[10:13], v[34:49]
	v_exp_f32_e32 v58, v58
	v_exp_f32_e32 v59, v59
	v_exp_f32_e32 v60, v60
	v_exp_f32_e32 v61, v61
	v_exp_f32_e32 v62, v62
	s_waitcnt lgkmcnt(12)
	v_mfma_f32_32x32x16_bf16 v[18:33], v[236:239], v[14:17], v[18:33]
	v_exp_f32_e32 v63, v63
	v_exp_f32_e32 v64, v64
	v_exp_f32_e32 v65, v65
	v_cvt_pk_bf16_f32 v248, v58, v59
	v_cvt_pk_bf16_f32 v249, v60, v61
	v_cvt_pk_bf16_f32 v250, v62, v63
	v_cvt_pk_bf16_f32 v251, v64, v65
	s_waitcnt lgkmcnt(10)
	v_mfma_f32_32x32x16_bf16 v[34:49], v[240:243], v[174:177], v[34:49]
	v_add_f32_e32 v4, v98, v100
	v_add_f32_e32 v9, v99, v101
	v_add_f32_e32 v6, v82, v84
	v_add_f32_e32 v7, v83, v85
	v_add_f32_e32 v4, v4, v102
	v_add_f32_e32 v9, v9, v103
	v_add_f32_e32 v6, v6, v86
	v_add_f32_e32 v7, v7, v87
	v_add_f32_e32 v4, v4, v104
	v_add_f32_e32 v9, v9, v105
	s_waitcnt lgkmcnt(8)
	v_mfma_f32_32x32x16_bf16 v[18:33], v[240:243], v[178:181], v[18:33]
	v_add_f32_e32 v6, v6, v88
	v_add_f32_e32 v7, v7, v89
	v_add_f32_e32 v4, v4, v106
	v_add_f32_e32 v9, v9, v107
	v_add_f32_e32 v6, v6, v90
	v_add_f32_e32 v7, v7, v91
	v_add_f32_e32 v4, v4, v108
	v_add_f32_e32 v9, v9, v109
	v_add_f32_e32 v6, v6, v92
	v_add_f32_e32 v7, v7, v93
	s_waitcnt lgkmcnt(6)
	v_mfma_f32_32x32x16_bf16 v[34:49], v[244:247], v[182:185], v[34:49]
	v_add_f32_e32 v4, v4, v110
	v_add_f32_e32 v9, v9, v111
	v_add_f32_e32 v6, v6, v94
	v_add_f32_e32 v7, v7, v95
	v_add_f32_e32 v4, v4, v112
	v_add_f32_e32 v9, v9, v113
	v_add_f32_e32 v6, v6, v96
	v_add_f32_e32 v7, v7, v97
	v_add_f32_e32 v6, v6, v7
	v_add_f32_e32 v4, v4, v9
	s_waitcnt lgkmcnt(4)
	v_mfma_f32_32x32x16_bf16 v[18:33], v[244:247], v[186:189], v[18:33]
	v_add_f32_e32 v4, v6, v4
	v_mov_b32_e32 v5, v4
	v_add_f32_e32 v225, v225, v4
	v_add_f32_e32 v4, v66, v68
	v_add_f32_e32 v9, v67, v69
	v_add_f32_e32 v6, v50, v52
	v_add_f32_e32 v7, v51, v53
	v_add_f32_e32 v4, v4, v70
	v_add_f32_e32 v9, v9, v71
	v_add_f32_e32 v6, v6, v54
	s_waitcnt lgkmcnt(2)
	v_mfma_f32_32x32x16_bf16 v[34:49], v[248:251], v[228:231], v[34:49]
	v_add_f32_e32 v7, v7, v55
	v_add_f32_e32 v4, v4, v72
	v_add_f32_e32 v9, v9, v73
	v_add_f32_e32 v6, v6, v56
	v_add_f32_e32 v7, v7, v57
	v_add_f32_e32 v4, v4, v74
	v_add_f32_e32 v9, v9, v75
	v_add_f32_e32 v6, v6, v58
	v_add_f32_e32 v7, v7, v59
	v_add_f32_e32 v4, v4, v76
	s_waitcnt lgkmcnt(0)
	v_mfma_f32_32x32x16_bf16 v[18:33], v[248:251], v[232:235], v[18:33]
	v_add_f32_e32 v9, v9, v77
	v_add_f32_e32 v6, v6, v60
	v_add_f32_e32 v7, v7, v61
	v_add_f32_e32 v4, v4, v78
	v_add_f32_e32 v9, v9, v79
	v_add_f32_e32 v6, v6, v62
	v_add_f32_e32 v7, v7, v63
	v_add_f32_e32 v4, v4, v80
	v_add_f32_e32 v9, v9, v81
	v_add_f32_e32 v6, v6, v64
	v_add_f32_e32 v7, v7, v65
	v_add_f32_e32 v6, v6, v7
	v_add_f32_e32 v4, v4, v9
	v_add_f32_e32 v4, v6, v4
	v_add_f32_e32 v225, v225, v4
	s_mov_b32 s30, 0x437f0000
	v_cmp_nge_f32_e32 vcc, s30, v5
	v_cmp_nge_f32_e64 s[98:99], s30, v4
	s_mov_b64 s[28:29], 0
	s_mov_b64 s[0:1], 0
	s_or_b64 s[98:99], vcc, s[98:99]
	s_cbranch_scc0 .LBB0_1492
	v_max3_f32 v5, v98, v99, v100
	v_max3_f32 v6, v106, v107, v108
	v_max3_f32 v9, v82, v83, v84
	v_max3_f32 v227, v90, v91, v92
	v_max3_f32 v5, v5, v101, v102
	v_max3_f32 v6, v6, v109, v110
	v_max3_f32 v9, v9, v85, v86
	v_max3_f32 v227, v227, v93, v94
	v_max3_f32 v5, v5, v103, v104
	v_max3_f32 v6, v6, v111, v112
	v_max3_f32 v9, v9, v87, v88
	v_max3_f32 v227, v227, v95, v96
	v_max3_f32 v5, v5, v105, v113
	v_max3_f32 v9, v9, v89, v97
	v_max3_f32 v5, v5, v6, v9
	v_max_f32_e32 v5, v5, v227
	v_mov_b32_e32 v6, v5
	s_nop 1
	v_permlane32_swap_b32_e32 v5, v6
	v_max_f32_e32 v5, v5, v6
	v_log_f32_e32 v5, v5
	s_nop 0
	v_cmp_lt_f32_e32 vcc, s74, v5
	s_and_b64 s[28:29], s[18:19], vcc
	v_cmp_lt_f32_e32 vcc, s75, v5
	s_or_b64 s[28:29], vcc, s[28:29]
	s_nop 0
	v_cndmask_b32_e64 v252, 0, v5, s[28:29]
	s_cselect_b64 s[28:29], -1, 0
	v_max3_f32 v5, v66, v67, v68
	v_max3_f32 v6, v74, v75, v76
	v_max3_f32 v9, v50, v51, v52
	v_max3_f32 v227, v58, v59, v60
	v_max3_f32 v5, v5, v69, v70
	v_max3_f32 v6, v6, v77, v78
	v_max3_f32 v9, v9, v53, v54
	v_max3_f32 v227, v227, v61, v62
	v_max3_f32 v5, v5, v71, v72
	v_max3_f32 v6, v6, v79, v80
	v_max3_f32 v9, v9, v55, v56
	v_max3_f32 v227, v227, v63, v64
	v_max3_f32 v5, v5, v73, v81
	v_max3_f32 v9, v9, v57, v65
	v_max3_f32 v5, v5, v6, v9
	v_max_f32_e32 v5, v5, v227
	v_mov_b32_e32 v6, v5
	s_nop 1
	v_permlane32_swap_b32_e32 v5, v6
	v_max_f32_e32 v5, v5, v6
	v_log_f32_e32 v5, v5
	s_nop 0
	v_cmp_lt_f32_e32 vcc, s74, v5
	s_and_b64 s[0:1], s[18:19], vcc
	v_cmp_lt_f32_e32 vcc, s75, v5
	s_or_b64 s[0:1], vcc, s[0:1]
	s_nop 0
	v_cndmask_b32_e64 v101, 0, v5, s[0:1]
	s_cselect_b64 s[0:1], -1, 0
	v_mov_b32_e32 v228, v252
	s_branch .LBB0_1492
.Lhb_full:
	s_lshl_b32 s30, s20, 13
	v_add_u32_e32 v8, s30, v169
	v_add_u32_e32 v3, s30, v193
	ds_read_b128 v[10:13], v8
	ds_read_b128 v[14:17], v8 offset:512
	ds_read_b128 v[174:177], v8 offset:2048
	ds_read_b128 v[178:181], v8 offset:2560
	ds_read_b128 v[182:185], v8 offset:4096
	ds_read_b128 v[186:189], v8 offset:4608
	ds_read_b128 v[228:231], v8 offset:6144
	ds_read_b128 v[232:235], v8 offset:6656
	v_cmp_eq_f32_e64 s[18:19], s73, v222
	s_mov_b64 s[20:21], 0
	s_nop 0
	v_cndmask_b32_e64 v7, -v222, v204, s[18:19]
	v_add_f32_e32 v82, v7, v9
	v_add_f32_e32 v50, v7, v4
	v_mov_b32_e32 v83, v82
	v_mov_b32_e32 v84, v82
	v_mov_b32_e32 v85, v82
	v_mov_b32_e32 v86, v82
	v_mov_b32_e32 v87, v82
	v_mov_b32_e32 v88, v82
	v_mov_b32_e32 v89, v82
	v_mov_b32_e32 v90, v82
	v_mov_b32_e32 v91, v82
	v_mov_b32_e32 v92, v82
	v_mov_b32_e32 v93, v82
	v_mov_b32_e32 v94, v82
	v_mov_b32_e32 v95, v82
	v_mov_b32_e32 v96, v82
	v_mov_b32_e32 v97, v82
	s_waitcnt lgkmcnt(7)
	s_nop 0
	v_mfma_f32_32x32x16_bf16 v[98:113], v[10:13], v[114:117], v[82:97]
	ds_read_b128 v[10:13], v8 offset:8192
	v_mov_b32_e32 v51, v50
	v_mov_b32_e32 v52, v50
	v_mov_b32_e32 v53, v50
	s_waitcnt lgkmcnt(7)
	v_mfma_f32_32x32x16_bf16 v[82:97], v[14:17], v[114:117], v[82:97]
	ds_read_b128 v[14:17], v8 offset:8704
	v_mov_b32_e32 v54, v50
	v_mov_b32_e32 v55, v50
	s_waitcnt lgkmcnt(7)
	v_mfma_f32_32x32x16_bf16 v[98:113], v[174:177], v[118:121], v[98:113]
	ds_read_b128 v[174:177], v8 offset:10240
	v_mov_b32_e32 v56, v50
	v_mov_b32_e32 v57, v50
	s_waitcnt lgkmcnt(7)
	v_mfma_f32_32x32x16_bf16 v[82:97], v[178:181], v[118:121], v[82:97]
	ds_read_b128 v[178:181], v8 offset:10752
	v_mov_b32_e32 v58, v50
	v_mov_b32_e32 v59, v50
	s_waitcnt lgkmcnt(7)
	v_mfma_f32_32x32x16_bf16 v[98:113], v[182:185], v[122:125], v[98:113]
	ds_read_b128 v[182:185], v8 offset:12288
	v_mov_b32_e32 v60, v50
	v_mov_b32_e32 v61, v50
	s_waitcnt lgkmcnt(7)
	v_mfma_f32_32x32x16_bf16 v[82:97], v[186:189], v[122:125], v[82:97]
	ds_read_b128 v[186:189], v8 offset:12800
	v_mov_b32_e32 v62, v50
	v_mov_b32_e32 v63, v50
	s_waitcnt lgkmcnt(7)
	v_mfma_f32_32x32x16_bf16 v[98:113], v[228:231], v[126:129], v[98:113]
	ds_read_b128 v[228:231], v8 offset:14336
	v_mov_b32_e32 v64, v50
	v_mov_b32_e32 v65, v50
	s_waitcnt lgkmcnt(7)
	v_mfma_f32_32x32x16_bf16 v[82:97], v[232:235], v[126:129], v[82:97]
	ds_read_b128 v[232:235], v8 offset:14848
	s_waitcnt lgkmcnt(7)
	v_mfma_f32_32x32x16_bf16 v[66:81], v[10:13], v[114:117], v[50:65]
	ds_read_b64_tr_b16 v[10:11], v3 offset:32768
	ds_read_b64_tr_b16 v[12:13], v3 offset:33280
	s_waitcnt lgkmcnt(8)
	v_mfma_f32_32x32x16_bf16 v[50:65], v[14:17], v[114:117], v[50:65]
	ds_read_b64_tr_b16 v[14:15], v3 offset:36864
	ds_read_b64_tr_b16 v[16:17], v3 offset:37376
	s_waitcnt lgkmcnt(9)
	v_mfma_f32_32x32x16_bf16 v[66:81], v[174:177], v[118:121], v[66:81]
	ds_read_b64_tr_b16 v[174:175], v3 offset:33792
	ds_read_b64_tr_b16 v[176:177], v3 offset:34304
	v_max3_f32 v5, v98, v99, v100
	v_max3_f32 v6, v106, v107, v108
	v_max3_f32 v9, v82, v83, v84
	v_max3_f32 v227, v90, v91, v92
	s_waitcnt lgkmcnt(10)
	v_mfma_f32_32x32x16_bf16 v[50:65], v[178:181], v[118:121], v[50:65]
	ds_read_b64_tr_b16 v[178:179], v3 offset:37888
	ds_read_b64_tr_b16 v[180:181], v3 offset:38400
	v_max3_f32 v5, v5, v101, v102
	v_max3_f32 v6, v6, v109, v110
	v_max3_f32 v9, v9, v85, v86
	v_max3_f32 v227, v227, v93, v94
	s_waitcnt lgkmcnt(11)
	v_mfma_f32_32x32x16_bf16 v[66:81], v[182:185], v[122:125], v[66:81]
	ds_read_b64_tr_b16 v[182:183], v3 offset:34816
	ds_read_b64_tr_b16 v[184:185], v3 offset:35328
	v_max3_f32 v5, v5, v103, v104
	v_max3_f32 v6, v6, v111, v112
	v_max3_f32 v9, v9, v87, v88
	v_max3_f32 v227, v227, v95, v96
	s_waitcnt lgkmcnt(12)
	v_mfma_f32_32x32x16_bf16 v[50:65], v[186:189], v[122:125], v[50:65]
	ds_read_b64_tr_b16 v[186:187], v3 offset:38912
	ds_read_b64_tr_b16 v[188:189], v3 offset:39424
	v_max3_f32 v5, v5, v105, v113
	v_max3_f32 v9, v9, v89, v97
	v_max3_f32 v5, v5, v6, v9
	v_max_f32_e32 v5, v5, v227
	v_mov_b32_e32 v6, v5
	s_waitcnt lgkmcnt(13)
	v_mfma_f32_32x32x16_bf16 v[66:81], v[228:231], v[126:129], v[66:81]
	ds_read_b64_tr_b16 v[228:229], v3 offset:35840
	ds_read_b64_tr_b16 v[230:231], v3 offset:36352
	v_exp_f32_e32 v98, v98
	v_exp_f32_e32 v99, v99
	v_permlane32_swap_b32_e32 v5, v6
	v_exp_f32_e32 v100, v100
	v_exp_f32_e32 v101, v101
	v_max_f32_e32 v5, v5, v6
	s_waitcnt lgkmcnt(14)
	v_mfma_f32_32x32x16_bf16 v[50:65], v[232:235], v[126:129], v[50:65]
	ds_read_b64_tr_b16 v[232:233], v3 offset:39936
	ds_read_b64_tr_b16 v[234:235], v3 offset:40448
	v_cmp_lt_f32_e32 vcc, s74, v5
	v_exp_f32_e32 v102, v102
	s_and_b64 s[28:29], s[18:19], vcc
	v_cmp_lt_f32_e32 vcc, s75, v5
	v_exp_f32_e32 v103, v103
	s_or_b64 s[28:29], vcc, s[28:29]
	v_exp_f32_e32 v104, v104
	v_cndmask_b32_e64 v252, 0, v5, s[28:29]
	s_cselect_b64 s[28:29], -1, 0
	v_exp_f32_e32 v105, v105
	v_cvt_pk_bf16_f32 v236, v98, v99
	v_cvt_pk_bf16_f32 v237, v100, v101
	v_cvt_pk_bf16_f32 v238, v102, v103
	v_cvt_pk_bf16_f32 v239, v104, v105
	v_exp_f32_e32 v106, v106
	v_exp_f32_e32 v107, v107
	s_waitcnt lgkmcnt(14)
	v_mfma_f32_32x32x16_bf16 v[34:49], v[236:239], v[10:13], v[34:49]
	ds_read_b64_tr_b16 v[10:11], v3 offset:40960
	ds_read_b64_tr_b16 v[12:13], v3 offset:41472
	v_exp_f32_e32 v108, v108
	v_exp_f32_e32 v109, v109
	v_exp_f32_e32 v110, v110
	v_exp_f32_e32 v111, v111
	v_exp_f32_e32 v112, v112
	v_exp_f32_e32 v113, v113
	s_waitcnt lgkmcnt(14)
	v_mfma_f32_32x32x16_bf16 v[18:33], v[236:239], v[14:17], v[18:33]
	ds_read_b64_tr_b16 v[14:15], v3 offset:45056
	ds_read_b64_tr_b16 v[16:17], v3 offset:45568
	v_cvt_pk_bf16_f32 v240, v106, v107
	v_cvt_pk_bf16_f32 v241, v108, v109
	v_cvt_pk_bf16_f32 v242, v110, v111
	v_cvt_pk_bf16_f32 v243, v112, v113
	v_exp_f32_e32 v82, v82
	v_exp_f32_e32 v83, v83
	s_waitcnt lgkmcnt(14)
	v_mfma_f32_32x32x16_bf16 v[34:49], v[240:243], v[174:177], v[34:49]
	ds_read_b64_tr_b16 v[174:175], v3 offset:41984
	ds_read_b64_tr_b16 v[176:177], v3 offset:42496
	v_exp_f32_e32 v84, v84
	v_exp_f32_e32 v85, v85
	v_exp_f32_e32 v86, v86
	v_exp_f32_e32 v87, v87
	v_exp_f32_e32 v88, v88
	v_exp_f32_e32 v89, v89
	s_waitcnt lgkmcnt(14)
	v_mfma_f32_32x32x16_bf16 v[18:33], v[240:243], v[178:181], v[18:33]
	ds_read_b64_tr_b16 v[178:179], v3 offset:46080
	ds_read_b64_tr_b16 v[180:181], v3 offset:46592
	v_cvt_pk_bf16_f32 v244, v82, v83
	v_cvt_pk_bf16_f32 v245, v84, v85
	v_cvt_pk_bf16_f32 v246, v86, v87
	v_cvt_pk_bf16_f32 v247, v88, v89
	v_exp_f32_e32 v90, v90
	v_exp_f32_e32 v91, v91
	s_waitcnt lgkmcnt(14)
	v_mfma_f32_32x32x16_bf16 v[34:49], v[244:247], v[182:185], v[34:49]
	ds_read_b64_tr_b16 v[182:183], v3 offset:43008
	ds_read_b64_tr_b16 v[184:185], v3 offset:43520
	v_exp_f32_e32 v92, v92
	v_exp_f32_e32 v93, v93
	v_exp_f32_e32 v94, v94
	v_exp_f32_e32 v95, v95
	v_exp_f32_e32 v96, v96
	v_exp_f32_e32 v97, v97
	s_waitcnt lgkmcnt(14)
	v_mfma_f32_32x32x16_bf16 v[18:33], v[244:247], v[186:189], v[18:33]
	ds_read_b64_tr_b16 v[186:187], v3 offset:47104
	ds_read_b64_tr_b16 v[188:189], v3 offset:47616
	v_cvt_pk_bf16_f32 v248, v90, v91
	v_cvt_pk_bf16_f32 v249, v92, v93
	v_cvt_pk_bf16_f32 v250, v94, v95
	v_cvt_pk_bf16_f32 v251, v96, v97
	v_add_f32_e32 v4, v98, v100
	v_add_f32_e32 v9, v99, v101
	v_add_f32_e32 v6, v82, v84
	v_add_f32_e32 v7, v83, v85
	v_add_f32_e32 v4, v4, v102
	v_add_f32_e32 v9, v9, v103
	s_waitcnt lgkmcnt(14)
	v_mfma_f32_32x32x16_bf16 v[34:49], v[248:251], v[228:231], v[34:49]
	ds_read_b64_tr_b16 v[228:229], v3 offset:44032
	ds_read_b64_tr_b16 v[230:231], v3 offset:44544
	v_add_f32_e32 v6, v6, v86
	v_add_f32_e32 v7, v7, v87
	v_add_f32_e32 v4, v4, v104
	v_add_f32_e32 v9, v9, v105
	v_add_f32_e32 v6, v6, v88
	v_add_f32_e32 v7, v7, v89
	v_add_f32_e32 v4, v4, v106
	v_add_f32_e32 v9, v9, v107
	v_add_f32_e32 v6, v6, v90
	v_add_f32_e32 v7, v7, v91
	v_add_f32_e32 v4, v4, v108
	v_add_f32_e32 v9, v9, v109
	s_waitcnt lgkmcnt(14)
	v_mfma_f32_32x32x16_bf16 v[18:33], v[248:251], v[232:235], v[18:33]
	ds_read_b64_tr_b16 v[232:233], v3 offset:48128
	ds_read_b64_tr_b16 v[234:235], v3 offset:48640
	v_add_f32_e32 v6, v6, v92
	v_add_f32_e32 v7, v7, v93
	v_add_f32_e32 v4, v4, v110
	v_add_f32_e32 v9, v9, v111
	v_add_f32_e32 v6, v6, v94
	v_add_f32_e32 v7, v7, v95
	v_add_f32_e32 v4, v4, v112
	v_add_f32_e32 v9, v9, v113
	v_add_f32_e32 v6, v6, v96
	v_add_f32_e32 v7, v7, v97
	v_add_f32_e32 v6, v6, v7
	v_add_f32_e32 v4, v4, v9
	v_add_f32_e32 v4, v6, v4
	v_add_f32_e32 v225, v225, v4
	v_max3_f32 v5, v66, v67, v68
	v_max3_f32 v6, v74, v75, v76
	v_max3_f32 v9, v50, v51, v52
	v_max3_f32 v227, v58, v59, v60
	v_max3_f32 v5, v5, v69, v70
	v_max3_f32 v6, v6, v77, v78
	v_max3_f32 v9, v9, v53, v54
	v_max3_f32 v227, v227, v61, v62
	v_max3_f32 v5, v5, v71, v72
	v_max3_f32 v6, v6, v79, v80
	v_max3_f32 v9, v9, v55, v56
	v_max3_f32 v227, v227, v63, v64
	v_max3_f32 v5, v5, v73, v81
	v_max3_f32 v9, v9, v57, v65
	v_max3_f32 v5, v5, v6, v9
	v_max_f32_e32 v5, v5, v227
	v_mov_b32_e32 v6, v5
	v_exp_f32_e32 v66, v66
	v_exp_f32_e32 v67, v67
	v_permlane32_swap_b32_e32 v5, v6
	v_exp_f32_e32 v68, v68
	v_exp_f32_e32 v69, v69
	v_max_f32_e32 v5, v5, v6
	v_cmp_lt_f32_e32 vcc, s74, v5
	v_exp_f32_e32 v70, v70
	s_and_b64 s[0:1], s[18:19], vcc
	v_cmp_lt_f32_e32 vcc, s75, v5
	v_exp_f32_e32 v71, v71
	s_or_b64 s[0:1], vcc, s[0:1]
	v_exp_f32_e32 v72, v72
	v_cndmask_b32_e64 v226, 0, v5, s[0:1]
	s_cselect_b64 s[0:1], -1, 0
	v_exp_f32_e32 v73, v73
	v_exp_f32_e32 v74, v74
	v_cvt_pk_bf16_f32 v236, v66, v67
	v_cvt_pk_bf16_f32 v237, v68, v69
	v_cvt_pk_bf16_f32 v238, v70, v71
	v_cvt_pk_bf16_f32 v239, v72, v73
	v_exp_f32_e32 v75, v75
	v_exp_f32_e32 v76, v76
	s_waitcnt lgkmcnt(14)
	v_mfma_f32_32x32x16_bf16 v[34:49], v[236:239], v[10:13], v[34:49]
	v_exp_f32_e32 v77, v77
	v_exp_f32_e32 v78, v78
	v_exp_f32_e32 v79, v79
	v_exp_f32_e32 v80, v80
	v_exp_f32_e32 v81, v81
	s_waitcnt lgkmcnt(12)
	v_mfma_f32_32x32x16_bf16 v[18:33], v[236:239], v[14:17], v[18:33]
	v_exp_f32_e32 v50, v50
	v_cvt_pk_bf16_f32 v240, v74, v75
	v_cvt_pk_bf16_f32 v241, v76, v77
	v_cvt_pk_bf16_f32 v242, v78, v79
	v_cvt_pk_bf16_f32 v243, v80, v81
	v_exp_f32_e32 v51, v51
	v_exp_f32_e32 v52, v52
	s_waitcnt lgkmcnt(10)
	v_mfma_f32_32x32x16_bf16 v[34:49], v[240:243], v[174:177], v[34:49]
	v_exp_f32_e32 v53, v53
	v_exp_f32_e32 v54, v54
	v_exp_f32_e32 v55, v55
	v_exp_f32_e32 v56, v56
	v_exp_f32_e32 v57, v57
	s_waitcnt lgkmcnt(8)
	v_mfma_f32_32x32x16_bf16 v[18:33], v[240:243], v[178:181], v[18:33]
	v_exp_f32_e32 v58, v58
	v_cvt_pk_bf16_f32 v244, v50, v51
	v_cvt_pk_bf16_f32 v245, v52, v53
	v_cvt_pk_bf16_f32 v246, v54, v55
	v_cvt_pk_bf16_f32 v247, v56, v57
	v_exp_f32_e32 v59, v59
	v_exp_f32_e32 v60, v60
	s_waitcnt lgkmcnt(6)
	v_mfma_f32_32x32x16_bf16 v[34:49], v[244:247], v[182:185], v[34:49]
	v_exp_f32_e32 v61, v61
	v_exp_f32_e32 v62, v62
	v_exp_f32_e32 v63, v63
	v_exp_f32_e32 v64, v64
	v_exp_f32_e32 v65, v65
	s_waitcnt lgkmcnt(4)
	v_mfma_f32_32x32x16_bf16 v[18:33], v[244:247], v[186:189], v[18:33]
	v_add_f32_e32 v4, v66, v68
	v_cvt_pk_bf16_f32 v248, v58, v59
	v_cvt_pk_bf16_f32 v249, v60, v61
	v_cvt_pk_bf16_f32 v250, v62, v63
	v_cvt_pk_bf16_f32 v251, v64, v65
	v_add_f32_e32 v9, v67, v69
	v_add_f32_e32 v6, v50, v52
	v_add_f32_e32 v7, v51, v53
	v_add_f32_e32 v4, v4, v70
	v_add_f32_e32 v9, v9, v71
	s_waitcnt lgkmcnt(2)
	v_mfma_f32_32x32x16_bf16 v[34:49], v[248:251], v[228:231], v[34:49]
	v_add_f32_e32 v6, v6, v54
	v_add_f32_e32 v7, v7, v55
	v_add_f32_e32 v4, v4, v72
	v_add_f32_e32 v9, v9, v73
	v_add_f32_e32 v6, v6, v56
	v_add_f32_e32 v7, v7, v57
	v_add_f32_e32 v4, v4, v74
	v_add_f32_e32 v9, v9, v75
	v_add_f32_e32 v6, v6, v58
	v_add_f32_e32 v7, v7, v59
	v_add_f32_e32 v4, v4, v76
	v_add_f32_e32 v9, v9, v77
	s_waitcnt lgkmcnt(0)
	v_mfma_f32_32x32x16_bf16 v[18:33], v[248:251], v[232:235], v[18:33]
	v_add_f32_e32 v6, v6, v60
	v_add_f32_e32 v7, v7, v61
	v_add_f32_e32 v4, v4, v78
	v_add_f32_e32 v9, v9, v79
	v_add_f32_e32 v6, v6, v62
	v_add_f32_e32 v7, v7, v63
	v_add_f32_e32 v4, v4, v80
	v_add_f32_e32 v9, v9, v81
	v_add_f32_e32 v6, v6, v64
	v_add_f32_e32 v7, v7, v65
	v_add_f32_e32 v6, v6, v7
	v_add_f32_e32 v4, v4, v9
	v_add_f32_e32 v4, v6, v4
	v_add_f32_e32 v225, v225, v4
	v_mov_b32_e32 v228, v252
	v_mov_b32_e32 v101, v226
	s_branch .LBB0_1492
